# phase 4: conv mixer after the SSD scan for all workgroups
# speedup vs baseline: 1.0155x; 1.0155x over previous
; __global__ void __launch_bounds__(NTHR, 2) mk_fwd(Args a_by_value) {
;     ...
;         } else if (PH_EN(4) && k == 4) {
;             unsigned* subc = (unsigned*)(ws + WS_BAR) + XCD_BAR_WORDS + 64 * (layer * 8);
;             for (int item = bid; item < 256; item += G) { ssd_bc_slice(a, layer, item); sub_arrive(subc + 64 * (item >> 5)); }
.LBB0_91:
	s_and_b64 vcc, exec, s[2:3]
	s_cbranch_vccz .LBB0_209
	s_mov_b32 s2, 1
	s_nop 0
	s_nop 1
	v_writelane_b32 v255, s2, 41
	s_lshl_b32 s2, s8, 9
	s_ashr_i32 s3, s2, 31
	s_lshl_b64 s[2:3], s[2:3], 2
	v_readlane_b32 s10, v253, 18
	s_add_u32 s2, s10, s2
	v_writelane_b32 v255, s2, 18
	v_readlane_b32 s2, v253, 19
	s_addc_u32 s11, s2, s3
	s_cmpk_lt_i32 s36, 0x100
	s_cselect_b64 s[28:29], -1, 0
	s_mov_b64 s[2:3], -1
	s_and_b64 vcc, exec, s[28:29]
	s_mul_hi_i32 s37, s8, 0x1800
	s_mul_i32 s88, s8, 0x1800
	s_cbranch_vccnz .LBB0_94
	s_ashr_i32 s2, s8, 31
	v_writelane_b32 v255, s2, 12
	s_mov_b64 s[2:3], 0
